# v23nopcut
# baseline (speedup 1.0000x reference)
; #define SBAR() __builtin_amdgcn_sched_barrier(0)
; #define PV_RD(F_, d0) do { constexpr int b_ = V_OFF + v_rd_off(d0, 0, 0); \
;         TRRD(F_[0], b_); TRRD(F_[1], b_ + 2048); TRRD(F_[2], b_ + 4096); TRRD(F_[3], b_ + 6144); TRRD(F_[4], b_ + 8192); TRRD(F_[5], b_ + 10240); TRRD(F_[6], b_ + 12288); TRRD(F_[7], b_ + 14336); } while (0)
; template <int k> __device__ __forceinline__ void par_snip(f32x16& p0, f32x16& p1, float& m_reg, float& pmax, float& alpha, float& mnL, float msk) {
;     constexpr float C2 = 1.4426950408889634f * SCALE;
;     if constexpr (k < 4) { constexpr int j = 4 * k; const float a = fmaxf(fmaxf(p0[j], p0[j + 1]), fmaxf(p0[j + 2], p0[j + 3])), b = fmaxf(fmaxf(p1[j], p1[j + 1]), fmaxf(p1[j + 2], p1[j + 3]));
;         pmax = (k == 0) ? fmaxf(a, b) : fmaxf(pmax, fmaxf(a, b)); }
;     else if constexpr (k == 4) { pmax += msk;
;         { auto rr = __builtin_amdgcn_permlane32_swap(__float_as_uint(pmax), __float_as_uint(pmax), false, false); pmax = fmaxf(__uint_as_float(rr[0]), __uint_as_float(rr[1])); }
;         const bool defer = __all((pmax - m_reg) * SCALE <= THR);
;         const float mn = defer ? m_reg : fmaxf(m_reg, pmax);
;         alpha = __builtin_amdgcn_exp2f((m_reg - mn) * C2); m_reg = mn; mnL = fmaf(-mn, C2, msk); }
;     else if constexpr (k < 9) { constexpr int j = 4 * (k - 5);
; #pragma unroll
;         for (int e = 0; e < 4; ++e) { p0[j + e] = fmaf(p0[j + e], C2, mnL); p1[j + e] = fmaf(p1[j + e], C2, mnL); } }
;     else if constexpr (k < 15) { constexpr int j = 2 * (k - 9); p0[j] = __builtin_amdgcn_exp2f(p0[j]); p0[j + 1] = __builtin_amdgcn_exp2f(p0[j + 1]); }
;     else if constexpr (k == 15) {
; #pragma unroll
;         for (int e = 12; e < 16; ++e) p0[e] = __builtin_amdgcn_exp2f(p0[e]); }
; __device__ __forceinline__ void stage_pv_par(f32x16* o, int vb0, bf16x8 pa0, bf16x8 pa1, bf16x8 pa2, bf16x8 pa3,
;                                              f32x16& x0, f32x16& x1, float& m_reg, float& alpha, float msk) {
;     ...
;     float pmax = 0.f, mnL = 0.f; s16x4 fA[8];
;     SBAR(); PV_RD(fA, 0); PV_WAIT(fA, 0); SBAR();
;     PVS(fA, 0); PV_RD(fA, 1); PV_WAIT(fA, 0); SBAR();
;     PVS(fA, 1); PV_RD(fA, 2); PV_WAIT(fA, 0); SBAR();
;     PVS(fA, 2); PV_RD(fA, 3); PV_WAIT(fA, 0); SBAR();
;     PVS(fA, 3);
.Lmy_mid_a:
	s_and_b32 s34, s85, 0xc000
	v_add_u32_e32 v217, s34, v225
	ds_read_b64_tr_b16 v[194:195], v217 offset:0
	ds_read_b64_tr_b16 v[196:197], v217 offset:0x800
	ds_read_b64_tr_b16 v[200:201], v217 offset:0x1000
	ds_read_b64_tr_b16 v[202:203], v217 offset:0x1800
	ds_read_b64_tr_b16 v[204:205], v217 offset:0x2000
	ds_read_b64_tr_b16 v[206:207], v217 offset:0x2800
	ds_read_b64_tr_b16 v[208:209], v217 offset:0x3000
	ds_read_b64_tr_b16 v[210:211], v217 offset:0x3800
	s_nop 0
	s_waitcnt lgkmcnt(0)
	s_nop 0
	v_mfma_f32_32x32x16_bf16 v[64:79], v[194:197], v[2:5], v[64:79]
	s_nop 5
	v_max3_f32 v0, v96, v97, v98
	v_max3_f32 v194, v112, v113, v114
	v_max3_f32 v0, v0, v99, v100
	v_max3_f32 v194, v194, v115, v116
	v_mfma_f32_32x32x16_bf16 v[64:79], v[200:203], v[6:9], v[64:79]
	v_max3_f32 v0, v0, v101, v102
	v_max3_f32 v194, v194, v117, v118
	v_max3_f32 v0, v0, v103, v104
	v_max3_f32 v194, v194, v119, v120
	v_mfma_f32_32x32x16_bf16 v[64:79], v[204:207], v[10:13], v[64:79]
	v_max3_f32 v0, v0, v105, v106
	v_max3_f32 v194, v194, v121, v122
	v_max3_f32 v0, v0, v107, v108
	v_max3_f32 v194, v194, v123, v124
	v_mfma_f32_32x32x16_bf16 v[64:79], v[208:211], v[176:179], v[64:79]
	v_max3_f32 v0, v0, v109, v110
	v_max3_f32 v194, v194, v125, v126
	v_max3_f32 v0, v0, v111, v127
	v_max_f32_e32 v0, v0, v194
	ds_read_b64_tr_b16 v[194:195], v217 offset:0x200
	ds_read_b64_tr_b16 v[196:197], v217 offset:0xa00
	ds_read_b64_tr_b16 v[200:201], v217 offset:0x1200
	ds_read_b64_tr_b16 v[202:203], v217 offset:0x1a00
	ds_read_b64_tr_b16 v[204:205], v217 offset:0x2200
	ds_read_b64_tr_b16 v[206:207], v217 offset:0x2a00
	ds_read_b64_tr_b16 v[208:209], v217 offset:0x3200
	ds_read_b64_tr_b16 v[210:211], v217 offset:0x3a00
	s_waitcnt lgkmcnt(0)
	v_add_f32_e32 v0, v216, v0
	v_mfma_f32_32x32x16_bf16 v[48:63], v[194:197], v[2:5], v[48:63]
	v_mov_b32_e32 v194, v0
	s_nop 1
	v_permlane32_swap_b32_e32 v0, v194
	v_max_f32_e32 v0, v0, v194
	v_sub_f32_e32 v194, v0, v244
	v_cmp_ge_f32_e32 vcc, 0x42ddb3d8, v194
	v_max_f32_e32 v0, v244, v0
	s_nop 0
	v_cndmask_b32_e32 v246, v0, v244, vcc
	v_sub_f32_e32 v0, v244, v246
	v_mul_f32_e32 v0, 0x3dd53b94, v0
	v_exp_f32_e32 v0, v0
	v_fmac_f32_e32 v216, 0xbdd53b94, v246
	v_mfma_f32_32x32x16_bf16 v[48:63], v[200:203], v[6:9], v[48:63]
	v_fmamk_f32 v96, v96, 0x3dd53b94, v216
	v_fmamk_f32 v97, v97, 0x3dd53b94, v216
	v_fmamk_f32 v98, v98, 0x3dd53b94, v216
	v_fmamk_f32 v99, v99, 0x3dd53b94, v216
	v_exp_f32_e32 v243, v96
	v_mfma_f32_32x32x16_bf16 v[48:63], v[204:207], v[10:13], v[48:63]
	v_fmamk_f32 v100, v100, 0x3dd53b94, v216
	v_fmamk_f32 v101, v101, 0x3dd53b94, v216
	v_exp_f32_e32 v242, v97
	v_exp_f32_e32 v241, v98
	v_mfma_f32_32x32x16_bf16 v[48:63], v[208:211], v[176:179], v[48:63]
	v_fmamk_f32 v102, v102, 0x3dd53b94, v216
	v_fmamk_f32 v103, v103, 0x3dd53b94, v216
	v_exp_f32_e32 v240, v99
	v_exp_f32_e32 v239, v100
	ds_read_b64_tr_b16 v[194:195], v217 offset:0x400
	ds_read_b64_tr_b16 v[196:197], v217 offset:0xc00
	ds_read_b64_tr_b16 v[200:201], v217 offset:0x1400
	ds_read_b64_tr_b16 v[202:203], v217 offset:0x1c00
	ds_read_b64_tr_b16 v[204:205], v217 offset:0x2400
	ds_read_b64_tr_b16 v[206:207], v217 offset:0x2c00
	ds_read_b64_tr_b16 v[208:209], v217 offset:0x3400
	ds_read_b64_tr_b16 v[210:211], v217 offset:0x3c00
	s_nop 0
	s_waitcnt lgkmcnt(0)
	s_nop 0
	v_mfma_f32_32x32x16_bf16 v[32:47], v[194:197], v[2:5], v[32:47]
	v_fmamk_f32 v104, v104, 0x3dd53b94, v216
	v_fmamk_f32 v105, v105, 0x3dd53b94, v216
	v_exp_f32_e32 v238, v101
	v_exp_f32_e32 v237, v102
	v_mfma_f32_32x32x16_bf16 v[32:47], v[200:203], v[6:9], v[32:47]
	v_fmamk_f32 v106, v106, 0x3dd53b94, v216
	v_fmamk_f32 v107, v107, 0x3dd53b94, v216
	v_exp_f32_e32 v236, v103
	v_exp_f32_e32 v235, v104
	v_mfma_f32_32x32x16_bf16 v[32:47], v[204:207], v[10:13], v[32:47]
	v_fmamk_f32 v108, v108, 0x3dd53b94, v216
	v_fmamk_f32 v109, v109, 0x3dd53b94, v216
	v_exp_f32_e32 v234, v105
	v_exp_f32_e32 v233, v106
	v_mfma_f32_32x32x16_bf16 v[32:47], v[208:211], v[176:179], v[32:47]
	v_fmamk_f32 v110, v110, 0x3dd53b94, v216
	v_fmamk_f32 v111, v111, 0x3dd53b94, v216
	v_exp_f32_e32 v232, v107
	v_exp_f32_e32 v231, v108
	ds_read_b64_tr_b16 v[194:195], v217 offset:0x600
	ds_read_b64_tr_b16 v[196:197], v217 offset:0xe00
	ds_read_b64_tr_b16 v[200:201], v217 offset:0x1600
	ds_read_b64_tr_b16 v[202:203], v217 offset:0x1e00
	ds_read_b64_tr_b16 v[204:205], v217 offset:0x2600
	ds_read_b64_tr_b16 v[206:207], v217 offset:0x2e00
	ds_read_b64_tr_b16 v[208:209], v217 offset:0x3600
	ds_read_b64_tr_b16 v[210:211], v217 offset:0x3e00
	s_nop 0
	s_waitcnt lgkmcnt(0)
	s_nop 0
	v_mfma_f32_32x32x16_bf16 v[16:31], v[194:197], v[2:5], v[16:31]
	v_exp_f32_e32 v230, v109
	v_fmamk_f32 v14, v112, 0x3dd53b94, v216
	v_fmamk_f32 v15, v113, 0x3dd53b94, v216
	v_fmamk_f32 v116, v116, 0x3dd53b94, v216
	v_fmamk_f32 v117, v117, 0x3dd53b94, v216
	v_mfma_f32_32x32x16_bf16 v[16:31], v[200:203], v[6:9], v[16:31]
	v_fmamk_f32 v118, v118, 0x3dd53b94, v216
	v_fmamk_f32 v119, v119, 0x3dd53b94, v216
	v_fmamk_f32 v120, v120, 0x3dd53b94, v216
	v_fmamk_f32 v121, v121, 0x3dd53b94, v216
	v_fmamk_f32 v122, v122, 0x3dd53b94, v216
	v_fmamk_f32 v123, v123, 0x3dd53b94, v216
	v_mfma_f32_32x32x16_bf16 v[16:31], v[204:207], v[10:13], v[16:31]
	v_fmamk_f32 v124, v124, 0x3dd53b94, v216
	v_fmamk_f32 v125, v125, 0x3dd53b94, v216
	v_fmamk_f32 v126, v126, 0x3dd53b94, v216
	v_fmamk_f32 v127, v127, 0x3dd53b94, v216
	v_mfma_f32_32x32x16_bf16 v[16:31], v[208:211], v[176:179], v[16:31]
	v_cmp_gt_f32_e32 vcc, 1.0, v0
	s_cbranch_vccz .LBB0_330
	v_pk_mul_f32 v[78:79], v[78:79], v[0:1] op_sel_hi:[1,0]
	v_pk_mul_f32 v[76:77], v[76:77], v[0:1] op_sel_hi:[1,0]
	v_pk_mul_f32 v[74:75], v[74:75], v[0:1] op_sel_hi:[1,0]
	v_pk_mul_f32 v[72:73], v[72:73], v[0:1] op_sel_hi:[1,0]
	v_pk_mul_f32 v[70:71], v[70:71], v[0:1] op_sel_hi:[1,0]
	v_pk_mul_f32 v[68:69], v[68:69], v[0:1] op_sel_hi:[1,0]
	v_pk_mul_f32 v[66:67], v[66:67], v[0:1] op_sel_hi:[1,0]
	v_pk_mul_f32 v[64:65], v[64:65], v[0:1] op_sel_hi:[1,0]
	v_pk_mul_f32 v[62:63], v[0:1], v[62:63] op_sel_hi:[0,1]
	v_pk_mul_f32 v[60:61], v[0:1], v[60:61] op_sel_hi:[0,1]
	v_pk_mul_f32 v[58:59], v[0:1], v[58:59] op_sel_hi:[0,1]
	v_pk_mul_f32 v[56:57], v[0:1], v[56:57] op_sel_hi:[0,1]
	v_pk_mul_f32 v[54:55], v[0:1], v[54:55] op_sel_hi:[0,1]
	v_pk_mul_f32 v[52:53], v[0:1], v[52:53] op_sel_hi:[0,1]
	v_pk_mul_f32 v[50:51], v[0:1], v[50:51] op_sel_hi:[0,1]
	v_pk_mul_f32 v[48:49], v[0:1], v[48:49] op_sel_hi:[0,1]
	v_pk_mul_f32 v[46:47], v[0:1], v[46:47] op_sel_hi:[0,1]
	v_pk_mul_f32 v[44:45], v[0:1], v[44:45] op_sel_hi:[0,1]
	v_pk_mul_f32 v[42:43], v[0:1], v[42:43] op_sel_hi:[0,1]
	v_pk_mul_f32 v[40:41], v[0:1], v[40:41] op_sel_hi:[0,1]
	v_pk_mul_f32 v[38:39], v[0:1], v[38:39] op_sel_hi:[0,1]
	v_pk_mul_f32 v[36:37], v[0:1], v[36:37] op_sel_hi:[0,1]
	v_pk_mul_f32 v[34:35], v[0:1], v[34:35] op_sel_hi:[0,1]
	v_pk_mul_f32 v[32:33], v[0:1], v[32:33] op_sel_hi:[0,1]
	v_pk_mul_f32 v[30:31], v[0:1], v[30:31] op_sel_hi:[0,1]
	v_pk_mul_f32 v[28:29], v[0:1], v[28:29] op_sel_hi:[0,1]
	v_pk_mul_f32 v[26:27], v[0:1], v[26:27] op_sel_hi:[0,1]
	v_pk_mul_f32 v[24:25], v[0:1], v[24:25] op_sel_hi:[0,1]
	v_pk_mul_f32 v[22:23], v[0:1], v[22:23] op_sel_hi:[0,1]
	v_pk_mul_f32 v[20:21], v[0:1], v[20:21] op_sel_hi:[0,1]
	v_pk_mul_f32 v[18:19], v[0:1], v[18:19] op_sel_hi:[0,1]
	v_pk_mul_f32 v[16:17], v[0:1], v[16:17] op_sel_hi:[0,1]

; #define SBAR() __builtin_amdgcn_sched_barrier(0)
; #define PV_RD(F_, d0) do { constexpr int b_ = V_OFF + v_rd_off(d0, 0, 0); \
;         TRRD(F_[0], b_); TRRD(F_[1], b_ + 2048); TRRD(F_[2], b_ + 4096); TRRD(F_[3], b_ + 6144); TRRD(F_[4], b_ + 8192); TRRD(F_[5], b_ + 10240); TRRD(F_[6], b_ + 12288); TRRD(F_[7], b_ + 14336); } while (0)
; template <int k> __device__ __forceinline__ void par_snip(f32x16& p0, f32x16& p1, float& m_reg, float& pmax, float& alpha, float& mnL, float msk) {
;     constexpr float C2 = 1.4426950408889634f * SCALE;
;     if constexpr (k < 4) { constexpr int j = 4 * k; const float a = fmaxf(fmaxf(p0[j], p0[j + 1]), fmaxf(p0[j + 2], p0[j + 3])), b = fmaxf(fmaxf(p1[j], p1[j + 1]), fmaxf(p1[j + 2], p1[j + 3]));
;         pmax = (k == 0) ? fmaxf(a, b) : fmaxf(pmax, fmaxf(a, b)); }
;     else if constexpr (k == 4) { pmax += msk;
;         { auto rr = __builtin_amdgcn_permlane32_swap(__float_as_uint(pmax), __float_as_uint(pmax), false, false); pmax = fmaxf(__uint_as_float(rr[0]), __uint_as_float(rr[1])); }
;         const bool defer = __all((pmax - m_reg) * SCALE <= THR);
;         const float mn = defer ? m_reg : fmaxf(m_reg, pmax);
;         alpha = __builtin_amdgcn_exp2f((m_reg - mn) * C2); m_reg = mn; mnL = fmaf(-mn, C2, msk); }
;     else if constexpr (k < 9) { constexpr int j = 4 * (k - 5);
; #pragma unroll
;         for (int e = 0; e < 4; ++e) { p0[j + e] = fmaf(p0[j + e], C2, mnL); p1[j + e] = fmaf(p1[j + e], C2, mnL); } }
;     else if constexpr (k < 15) { constexpr int j = 2 * (k - 9); p0[j] = __builtin_amdgcn_exp2f(p0[j]); p0[j + 1] = __builtin_amdgcn_exp2f(p0[j + 1]); }
;     else if constexpr (k == 15) {
; #pragma unroll
;         for (int e = 12; e < 16; ++e) p0[e] = __builtin_amdgcn_exp2f(p0[e]); }
; __device__ __forceinline__ void stage_pv_par(f32x16* o, int vb0, bf16x8 pa0, bf16x8 pa1, bf16x8 pa2, bf16x8 pa3,
;                                              f32x16& x0, f32x16& x1, float& m_reg, float& alpha, float msk) {
;     ...
;     float pmax = 0.f, mnL = 0.f; s16x4 fA[8];
;     SBAR(); PV_RD(fA, 0); PV_WAIT(fA, 0); SBAR();
;     PVS(fA, 0); PV_RD(fA, 1); PV_WAIT(fA, 0); SBAR();
;     PVS(fA, 1); PV_RD(fA, 2); PV_WAIT(fA, 0); SBAR();
;     PVS(fA, 2); PV_RD(fA, 3); PV_WAIT(fA, 0); SBAR();
;     PVS(fA, 3);
.Lmy_mid_b:
	s_and_b32 s34, s34, 0xc000
	v_add_u32_e32 v217, s34, v225
	ds_read_b64_tr_b16 v[194:195], v217 offset:0
	ds_read_b64_tr_b16 v[196:197], v217 offset:0x800
	ds_read_b64_tr_b16 v[232:233], v217 offset:0x1000
	ds_read_b64_tr_b16 v[234:235], v217 offset:0x1800
	ds_read_b64_tr_b16 v[236:237], v217 offset:0x2000
	ds_read_b64_tr_b16 v[238:239], v217 offset:0x2800
	ds_read_b64_tr_b16 v[240:241], v217 offset:0x3000
	ds_read_b64_tr_b16 v[242:243], v217 offset:0x3800
	s_nop 0
	s_waitcnt lgkmcnt(0)
	s_nop 0
	v_mfma_f32_32x32x16_bf16 v[64:79], v[194:197], v[2:5], v[64:79]
	s_nop 5
	v_max3_f32 v192, v96, v97, v98
	v_max3_f32 v194, v80, v81, v82
	v_max3_f32 v192, v192, v99, v100
	v_max3_f32 v194, v194, v83, v84
	v_mfma_f32_32x32x16_bf16 v[64:79], v[232:235], v[6:9], v[64:79]
	v_max3_f32 v192, v192, v101, v102
	v_max3_f32 v194, v194, v85, v86
	v_max3_f32 v192, v192, v103, v104
	v_max3_f32 v194, v194, v87, v88
	v_mfma_f32_32x32x16_bf16 v[64:79], v[236:239], v[10:13], v[64:79]
	v_max3_f32 v192, v192, v105, v106
	v_max3_f32 v194, v194, v89, v90
	v_max3_f32 v192, v192, v107, v108
	v_max3_f32 v194, v194, v91, v92
	v_mfma_f32_32x32x16_bf16 v[64:79], v[240:243], v[112:115], v[64:79]
	v_max3_f32 v192, v192, v109, v110
	v_max3_f32 v194, v194, v93, v94
	v_max3_f32 v192, v192, v111, v95
	v_max_f32_e32 v192, v192, v194
	ds_read_b64_tr_b16 v[194:195], v217 offset:0x200
	ds_read_b64_tr_b16 v[196:197], v217 offset:0xa00
	ds_read_b64_tr_b16 v[232:233], v217 offset:0x1200
	ds_read_b64_tr_b16 v[234:235], v217 offset:0x1a00
	ds_read_b64_tr_b16 v[236:237], v217 offset:0x2200
	ds_read_b64_tr_b16 v[238:239], v217 offset:0x2a00
	ds_read_b64_tr_b16 v[240:241], v217 offset:0x3200
	ds_read_b64_tr_b16 v[242:243], v217 offset:0x3a00
	s_waitcnt lgkmcnt(0)
	v_add_f32_e32 v192, v178, v192
	v_mfma_f32_32x32x16_bf16 v[48:63], v[194:197], v[2:5], v[48:63]
	v_mov_b32_e32 v194, v192
	s_nop 1
	v_permlane32_swap_b32_e32 v192, v194
	v_max_f32_e32 v192, v192, v194
	v_sub_f32_e32 v194, v192, v246
	v_cmp_ge_f32_e32 vcc, 0x42ddb3d8, v194
	v_max_f32_e32 v192, v246, v192
	s_nop 0
	v_cndmask_b32_e32 v244, v192, v246, vcc
	v_sub_f32_e32 v192, v246, v244
	v_mul_f32_e32 v192, 0x3dd53b94, v192
	v_exp_f32_e32 v192, v192
	v_fmac_f32_e32 v178, 0xbdd53b94, v244
	v_mfma_f32_32x32x16_bf16 v[48:63], v[232:235], v[6:9], v[48:63]
	v_fmamk_f32 v214, v80, 0x3dd53b94, v178
	v_fmamk_f32 v215, v81, 0x3dd53b94, v178
	v_fmamk_f32 v212, v82, 0x3dd53b94, v178
	v_fmamk_f32 v213, v83, 0x3dd53b94, v178
	v_fmamk_f32 v210, v84, 0x3dd53b94, v178
	v_fmamk_f32 v211, v85, 0x3dd53b94, v178
	v_mfma_f32_32x32x16_bf16 v[48:63], v[236:239], v[10:13], v[48:63]
	v_fmamk_f32 v208, v86, 0x3dd53b94, v178
	v_fmamk_f32 v209, v87, 0x3dd53b94, v178
	v_fmamk_f32 v206, v88, 0x3dd53b94, v178
	v_fmamk_f32 v207, v89, 0x3dd53b94, v178
	v_fmamk_f32 v204, v90, 0x3dd53b94, v178
	v_fmamk_f32 v205, v91, 0x3dd53b94, v178
	v_mfma_f32_32x32x16_bf16 v[48:63], v[240:243], v[112:115], v[48:63]
	v_fmamk_f32 v202, v92, 0x3dd53b94, v178
	v_fmamk_f32 v203, v93, 0x3dd53b94, v178
	v_fmamk_f32 v200, v94, 0x3dd53b94, v178
	v_fmamk_f32 v201, v95, 0x3dd53b94, v178
	v_fmamk_f32 v96, v96, 0x3dd53b94, v178
	v_fmamk_f32 v97, v97, 0x3dd53b94, v178
	ds_read_b64_tr_b16 v[194:195], v217 offset:0x400
	ds_read_b64_tr_b16 v[196:197], v217 offset:0xc00
	ds_read_b64_tr_b16 v[232:233], v217 offset:0x1400
	ds_read_b64_tr_b16 v[234:235], v217 offset:0x1c00
	ds_read_b64_tr_b16 v[236:237], v217 offset:0x2400
	ds_read_b64_tr_b16 v[238:239], v217 offset:0x2c00
	ds_read_b64_tr_b16 v[240:241], v217 offset:0x3400
	ds_read_b64_tr_b16 v[242:243], v217 offset:0x3c00
	s_nop 0
	s_waitcnt lgkmcnt(0)
	s_nop 0
	v_mfma_f32_32x32x16_bf16 v[32:47], v[194:197], v[2:5], v[32:47]
	v_fmamk_f32 v98, v98, 0x3dd53b94, v178
	v_fmamk_f32 v99, v99, 0x3dd53b94, v178
	v_exp_f32_e32 v80, v96
	v_exp_f32_e32 v81, v97
	v_mfma_f32_32x32x16_bf16 v[32:47], v[232:235], v[6:9], v[32:47]
	v_fmamk_f32 v100, v100, 0x3dd53b94, v178
	v_fmamk_f32 v101, v101, 0x3dd53b94, v178
	v_exp_f32_e32 v82, v98
	v_exp_f32_e32 v83, v99
	v_mfma_f32_32x32x16_bf16 v[32:47], v[236:239], v[10:13], v[32:47]
	v_fmamk_f32 v102, v102, 0x3dd53b94, v178
	v_fmamk_f32 v103, v103, 0x3dd53b94, v178
	v_exp_f32_e32 v84, v100
	v_exp_f32_e32 v85, v101
	v_mfma_f32_32x32x16_bf16 v[32:47], v[240:243], v[112:115], v[32:47]
	v_fmamk_f32 v104, v104, 0x3dd53b94, v178
	v_fmamk_f32 v105, v105, 0x3dd53b94, v178
	v_exp_f32_e32 v86, v102
	v_exp_f32_e32 v87, v103
	ds_read_b64_tr_b16 v[194:195], v217 offset:0x600
	ds_read_b64_tr_b16 v[196:197], v217 offset:0xe00
	ds_read_b64_tr_b16 v[232:233], v217 offset:0x1600
	ds_read_b64_tr_b16 v[234:235], v217 offset:0x1e00
	ds_read_b64_tr_b16 v[236:237], v217 offset:0x2600
	ds_read_b64_tr_b16 v[238:239], v217 offset:0x2e00
	ds_read_b64_tr_b16 v[240:241], v217 offset:0x3600
	ds_read_b64_tr_b16 v[242:243], v217 offset:0x3e00
	s_nop 0
	s_waitcnt lgkmcnt(0)
	s_nop 0
	v_mfma_f32_32x32x16_bf16 v[16:31], v[194:197], v[2:5], v[16:31]
	v_fmamk_f32 v106, v106, 0x3dd53b94, v178
	v_fmamk_f32 v107, v107, 0x3dd53b94, v178
	v_exp_f32_e32 v88, v104
	v_exp_f32_e32 v89, v105
	v_mfma_f32_32x32x16_bf16 v[16:31], v[232:235], v[6:9], v[16:31]
	v_fmamk_f32 v108, v108, 0x3dd53b94, v178
	v_fmamk_f32 v109, v109, 0x3dd53b94, v178
	v_exp_f32_e32 v90, v106
	v_exp_f32_e32 v91, v107
	v_mfma_f32_32x32x16_bf16 v[16:31], v[236:239], v[10:13], v[16:31]
	v_fmamk_f32 v110, v110, 0x3dd53b94, v178
	v_fmamk_f32 v111, v111, 0x3dd53b94, v178
	v_exp_f32_e32 v92, v108
	v_exp_f32_e32 v93, v109
	v_mfma_f32_32x32x16_bf16 v[16:31], v[240:243], v[112:115], v[16:31]
	v_cmp_gt_f32_e32 vcc, 1.0, v192
	s_cbranch_vccz .LBB0_335
	v_pk_mul_f32 v[78:79], v[78:79], v[192:193] op_sel_hi:[1,0]
	v_pk_mul_f32 v[76:77], v[76:77], v[192:193] op_sel_hi:[1,0]
	v_pk_mul_f32 v[74:75], v[74:75], v[192:193] op_sel_hi:[1,0]
	v_pk_mul_f32 v[72:73], v[72:73], v[192:193] op_sel_hi:[1,0]
	v_pk_mul_f32 v[70:71], v[70:71], v[192:193] op_sel_hi:[1,0]
	v_pk_mul_f32 v[68:69], v[68:69], v[192:193] op_sel_hi:[1,0]
	v_pk_mul_f32 v[66:67], v[66:67], v[192:193] op_sel_hi:[1,0]
	v_pk_mul_f32 v[64:65], v[64:65], v[192:193] op_sel_hi:[1,0]
	v_pk_mul_f32 v[62:63], v[192:193], v[62:63] op_sel_hi:[0,1]
	v_pk_mul_f32 v[60:61], v[192:193], v[60:61] op_sel_hi:[0,1]
	v_pk_mul_f32 v[58:59], v[192:193], v[58:59] op_sel_hi:[0,1]
	v_pk_mul_f32 v[56:57], v[192:193], v[56:57] op_sel_hi:[0,1]
	v_pk_mul_f32 v[54:55], v[192:193], v[54:55] op_sel_hi:[0,1]
	v_pk_mul_f32 v[52:53], v[192:193], v[52:53] op_sel_hi:[0,1]
	v_pk_mul_f32 v[50:51], v[192:193], v[50:51] op_sel_hi:[0,1]
	v_pk_mul_f32 v[48:49], v[192:193], v[48:49] op_sel_hi:[0,1]
	v_pk_mul_f32 v[46:47], v[192:193], v[46:47] op_sel_hi:[0,1]
	v_pk_mul_f32 v[44:45], v[192:193], v[44:45] op_sel_hi:[0,1]
	v_pk_mul_f32 v[42:43], v[192:193], v[42:43] op_sel_hi:[0,1]
	v_pk_mul_f32 v[40:41], v[192:193], v[40:41] op_sel_hi:[0,1]
	v_pk_mul_f32 v[38:39], v[192:193], v[38:39] op_sel_hi:[0,1]
	v_pk_mul_f32 v[36:37], v[192:193], v[36:37] op_sel_hi:[0,1]
	v_pk_mul_f32 v[34:35], v[192:193], v[34:35] op_sel_hi:[0,1]
	v_pk_mul_f32 v[32:33], v[192:193], v[32:33] op_sel_hi:[0,1]
	v_pk_mul_f32 v[30:31], v[192:193], v[30:31] op_sel_hi:[0,1]
	v_pk_mul_f32 v[28:29], v[192:193], v[28:29] op_sel_hi:[0,1]
	v_pk_mul_f32 v[26:27], v[192:193], v[26:27] op_sel_hi:[0,1]
	v_pk_mul_f32 v[24:25], v[192:193], v[24:25] op_sel_hi:[0,1]
	v_pk_mul_f32 v[22:23], v[192:193], v[22:23] op_sel_hi:[0,1]
	v_pk_mul_f32 v[20:21], v[192:193], v[20:21] op_sel_hi:[0,1]
	v_pk_mul_f32 v[18:19], v[192:193], v[18:19] op_sel_hi:[0,1]
	v_pk_mul_f32 v[16:17], v[192:193], v[16:17] op_sel_hi:[0,1]
